# prologue filter generation: the w3 accumulation loop keeps 4 iterations (32 loads) in flight instead of waiting on each group of 4 loads right after issuing it
# baseline (speedup 1.0000x reference)
; DI void filter_item(const Params& p, int layer, int L, int tile, char* smem) {
;     ...
;   float ps0 = 0.f, ps1 = 0.f;
;   float fa[16][4];
; #pragma unroll
;   for (int ml = 0; ml < 16; ++ml) { fa[ml][0] = 0.f; fa[ml][1] = 0.f; fa[ml][2] = 0.f; fa[ml][3] = 0.f; }
;   for (int e = 0; e < 64; ++e) {
;     const float* wr = w3 + e * 1024 + ch;
;     const float w0 = wr[0], w1v = wr[256], w2v = wr[512], w3v = wr[768];
; #pragma unroll
;     for (int ml = 0; ml < 16; ++ml) {
;       const float hv = h2[ml * 64 + e];
;       fa[ml][0] += hv * w0; fa[ml][1] += hv * w1v; fa[ml][2] += hv * w2v; fa[ml][3] += hv * w3v;
;     }
;   }
.LBB0_126:
	s_or_b64 exec, exec, s[36:37]
	v_ashrrev_i32_e32 v17, 31, v16
	v_mov_b32_e32 v18, 0
	v_lshl_add_u64 v[44:45], v[16:17], 2, s[74:75]
	s_movk_i32 s36, 0x1840
	s_mov_b64 s[0:1], 0
	v_mov_b32_e32 v19, v18
	v_mov_b32_e32 v20, v18
	v_mov_b32_e32 v21, v18
	v_mov_b32_e32 v22, v18
	v_mov_b32_e32 v23, v18
	v_mov_b32_e32 v8, v18
	v_mov_b32_e32 v9, v18
	v_mov_b32_e32 v24, v18
	v_mov_b32_e32 v25, v18
	v_mov_b32_e32 v26, v18
	v_mov_b32_e32 v27, v18
	v_mov_b32_e32 v28, v18
	v_mov_b32_e32 v29, v18
	v_mov_b32_e32 v10, v18
	v_mov_b32_e32 v11, v18
	v_mov_b32_e32 v30, v18
	v_mov_b32_e32 v31, v18
	v_mov_b32_e32 v32, v18
	v_mov_b32_e32 v33, v18
	v_mov_b32_e32 v34, v18
	v_mov_b32_e32 v35, v18
	v_mov_b32_e32 v4, v18
	v_mov_b32_e32 v5, v18
	v_mov_b32_e32 v36, v18
	v_mov_b32_e32 v37, v18
	v_mov_b32_e32 v38, v18
	v_mov_b32_e32 v39, v18
	v_mov_b32_e32 v40, v18
	v_mov_b32_e32 v41, v18
	v_mov_b32_e32 v6, v18
	v_mov_b32_e32 v7, v18
	v_mov_b32_e32 v42, v18
	v_mov_b32_e32 v43, v18
	v_mov_b32_e32 v46, v18
	v_mov_b32_e32 v47, v18
	v_mov_b32_e32 v50, v18
	v_mov_b32_e32 v51, v18
	v_mov_b32_e32 v0, v18
	v_mov_b32_e32 v1, v18
	v_mov_b32_e32 v56, v18
	v_mov_b32_e32 v57, v18
	v_mov_b32_e32 v58, v18
	v_mov_b32_e32 v59, v18
	v_mov_b32_e32 v60, v18
	v_mov_b32_e32 v61, v18
	v_mov_b32_e32 v2, v18
	v_mov_b32_e32 v3, v18
	v_mov_b32_e32 v62, v18
	v_mov_b32_e32 v63, v18
	v_mov_b32_e32 v64, v18
	v_mov_b32_e32 v65, v18
	v_mov_b32_e32 v66, v18
	v_mov_b32_e32 v67, v18
	v_mov_b32_e32 v54, v18
	v_mov_b32_e32 v55, v18
	v_mov_b32_e32 v52, v18
	v_mov_b32_e32 v53, v18
	v_mov_b32_e32 v68, v18
	v_mov_b32_e32 v69, v18
	v_mov_b32_e32 v70, v18
	v_mov_b32_e32 v71, v18
	v_mov_b32_e32 v72, v18
	v_mov_b32_e32 v73, v18
	s_waitcnt lgkmcnt(0)
	s_barrier
	s_mov_b32 s101, 0
	s_mov_b32 s100, 0x0
	v_lshl_add_u64 v[176:177], v[44:45], 0, s[100:101]
	global_load_dword v145, v[176:177], off
	global_load_dword v144, v[176:177], off offset:1024
	global_load_dword v147, v[176:177], off offset:2048
	global_load_dword v146, v[176:177], off offset:3072
	v_add_co_u32_e32 v178, vcc, 0x1000, v176
	v_addc_co_u32_e32 v179, vcc, 0, v177, vcc
	global_load_dword v149, v[178:179], off
	global_load_dword v148, v[178:179], off offset:1024
	global_load_dword v151, v[178:179], off offset:2048
	global_load_dword v150, v[178:179], off offset:3072
	s_mov_b32 s100, 0x2000
	v_lshl_add_u64 v[176:177], v[44:45], 0, s[100:101]
	global_load_dword v153, v[176:177], off
	global_load_dword v152, v[176:177], off offset:1024
	global_load_dword v155, v[176:177], off offset:2048
	global_load_dword v154, v[176:177], off offset:3072
	v_add_co_u32_e32 v178, vcc, 0x1000, v176
	v_addc_co_u32_e32 v179, vcc, 0, v177, vcc
	global_load_dword v157, v[178:179], off
	global_load_dword v156, v[178:179], off offset:1024
	global_load_dword v159, v[178:179], off offset:2048
	global_load_dword v158, v[178:179], off offset:3072
	s_mov_b32 s100, 0x4000
	v_lshl_add_u64 v[176:177], v[44:45], 0, s[100:101]
	global_load_dword v161, v[176:177], off
	global_load_dword v160, v[176:177], off offset:1024
	global_load_dword v163, v[176:177], off offset:2048
	global_load_dword v162, v[176:177], off offset:3072
	v_add_co_u32_e32 v178, vcc, 0x1000, v176
	v_addc_co_u32_e32 v179, vcc, 0, v177, vcc
	global_load_dword v165, v[178:179], off
	global_load_dword v164, v[178:179], off offset:1024
	global_load_dword v167, v[178:179], off offset:2048
	global_load_dword v166, v[178:179], off offset:3072
	s_mov_b32 s100, 0x6000
	v_lshl_add_u64 v[176:177], v[44:45], 0, s[100:101]
	global_load_dword v169, v[176:177], off
	global_load_dword v168, v[176:177], off offset:1024
	global_load_dword v171, v[176:177], off offset:2048
	global_load_dword v170, v[176:177], off offset:3072
	v_add_co_u32_e32 v178, vcc, 0x1000, v176
	v_addc_co_u32_e32 v179, vcc, 0, v177, vcc
	global_load_dword v173, v[178:179], off
	global_load_dword v172, v[178:179], off offset:1024
	global_load_dword v175, v[178:179], off offset:2048
	global_load_dword v174, v[178:179], off offset:3072
.LBB0_127:
	v_mov_b32_e32 v12, s36
	ds_read2_b64 v[80:83], v12 offset1:32
	ds_read2_b64 v[84:87], v12 offset0:64 offset1:96
	ds_read2_b64 v[88:91], v12 offset0:128 offset1:160
	ds_read2_b64 v[92:95], v12 offset0:192 offset1:224
	v_add_u32_e32 v12, 0x800, v12
	ds_read2_b64 v[96:99], v12 offset1:32
	ds_read2_b64 v[100:103], v12 offset0:64 offset1:96
	ds_read2_b64 v[104:107], v12 offset0:128 offset1:160
	ds_read2_b64 v[108:111], v12 offset0:192 offset1:224
	s_add_i32 s36, s36, 8
	s_waitcnt vmcnt(24) lgkmcnt(7)
	v_pk_fma_f32 v[72:73], v[144:145], v[80:81], v[72:73] op_sel_hi:[1,0,1]
	v_pk_fma_f32 v[68:69], v[144:145], v[82:83], v[68:69] op_sel_hi:[1,0,1]
	v_pk_fma_f32 v[70:71], v[146:147], v[80:81], v[70:71] op_sel_hi:[1,0,1]
	v_pk_fma_f32 v[52:53], v[146:147], v[82:83], v[52:53] op_sel_hi:[1,0,1]
	s_waitcnt lgkmcnt(6)
	v_pk_fma_f32 v[54:55], v[144:145], v[84:85], v[54:55] op_sel_hi:[1,0,1]
	v_pk_fma_f32 v[66:67], v[146:147], v[84:85], v[66:67] op_sel_hi:[1,0,1]
	v_pk_fma_f32 v[64:65], v[144:145], v[86:87], v[64:65] op_sel_hi:[1,0,1]
	v_pk_fma_f32 v[62:63], v[146:147], v[86:87], v[62:63] op_sel_hi:[1,0,1]
	s_waitcnt lgkmcnt(5)
	v_pk_fma_f32 v[2:3], v[144:145], v[88:89], v[2:3] op_sel_hi:[1,0,1]
	v_pk_fma_f32 v[60:61], v[146:147], v[88:89], v[60:61] op_sel_hi:[1,0,1]
	v_pk_fma_f32 v[58:59], v[144:145], v[90:91], v[58:59] op_sel_hi:[1,0,1]
	v_pk_fma_f32 v[56:57], v[146:147], v[90:91], v[56:57] op_sel_hi:[1,0,1]
	s_waitcnt lgkmcnt(4)
	v_pk_fma_f32 v[0:1], v[144:145], v[92:93], v[0:1] op_sel_hi:[1,0,1]
	v_pk_fma_f32 v[50:51], v[146:147], v[92:93], v[50:51] op_sel_hi:[1,0,1]
	v_pk_fma_f32 v[46:47], v[144:145], v[94:95], v[46:47] op_sel_hi:[1,0,1]
	v_pk_fma_f32 v[42:43], v[146:147], v[94:95], v[42:43] op_sel_hi:[1,0,1]
	s_waitcnt lgkmcnt(3)
; DI void filter_item(const Params& p, int layer, int L, int tile, char* smem) {
;     ...
;   for (int e = 0; e < 64; ++e) {
;     const float* wr = w3 + e * 1024 + ch;
;     const float w0 = wr[0], w1v = wr[256], w2v = wr[512], w3v = wr[768];
; #pragma unroll
;     for (int ml = 0; ml < 16; ++ml) {
;       const float hv = h2[ml * 64 + e];
;       fa[ml][0] += hv * w0; fa[ml][1] += hv * w1v; fa[ml][2] += hv * w2v; fa[ml][3] += hv * w3v;
;     }
;   }
	v_pk_fma_f32 v[6:7], v[144:145], v[96:97], v[6:7] op_sel_hi:[1,0,1]
	v_pk_fma_f32 v[40:41], v[146:147], v[96:97], v[40:41] op_sel_hi:[1,0,1]
	v_pk_fma_f32 v[38:39], v[144:145], v[98:99], v[38:39] op_sel_hi:[1,0,1]
	v_pk_fma_f32 v[36:37], v[146:147], v[98:99], v[36:37] op_sel_hi:[1,0,1]
	s_waitcnt lgkmcnt(2)
	v_pk_fma_f32 v[4:5], v[144:145], v[100:101], v[4:5] op_sel_hi:[1,0,1]
	v_pk_fma_f32 v[34:35], v[146:147], v[100:101], v[34:35] op_sel_hi:[1,0,1]
	v_pk_fma_f32 v[32:33], v[144:145], v[102:103], v[32:33] op_sel_hi:[1,0,1]
	v_pk_fma_f32 v[30:31], v[146:147], v[102:103], v[30:31] op_sel_hi:[1,0,1]
	s_waitcnt lgkmcnt(1)
	v_pk_fma_f32 v[10:11], v[144:145], v[104:105], v[10:11] op_sel_hi:[1,0,1]
	v_pk_fma_f32 v[28:29], v[146:147], v[104:105], v[28:29] op_sel_hi:[1,0,1]
	v_pk_fma_f32 v[26:27], v[144:145], v[106:107], v[26:27] op_sel_hi:[1,0,1]
	v_pk_fma_f32 v[24:25], v[146:147], v[106:107], v[24:25] op_sel_hi:[1,0,1]
	s_waitcnt lgkmcnt(0)
	v_pk_fma_f32 v[8:9], v[144:145], v[108:109], v[8:9] op_sel_hi:[1,0,1]
	v_pk_fma_f32 v[22:23], v[146:147], v[108:109], v[22:23] op_sel_hi:[1,0,1]
	v_pk_fma_f32 v[20:21], v[144:145], v[110:111], v[20:21] op_sel_hi:[1,0,1]
	v_pk_fma_f32 v[18:19], v[146:147], v[110:111], v[18:19] op_sel_hi:[1,0,1]
	v_pk_fma_f32 v[72:73], v[148:149], v[80:81], v[72:73] op_sel:[0,1,0]
	v_pk_fma_f32 v[68:69], v[148:149], v[82:83], v[68:69] op_sel:[0,1,0]
	v_pk_fma_f32 v[70:71], v[150:151], v[80:81], v[70:71] op_sel:[0,1,0]
	v_pk_fma_f32 v[52:53], v[150:151], v[82:83], v[52:53] op_sel:[0,1,0]
	v_pk_fma_f32 v[54:55], v[148:149], v[84:85], v[54:55] op_sel:[0,1,0]
	v_pk_fma_f32 v[66:67], v[150:151], v[84:85], v[66:67] op_sel:[0,1,0]
	v_pk_fma_f32 v[64:65], v[148:149], v[86:87], v[64:65] op_sel:[0,1,0]
	v_pk_fma_f32 v[62:63], v[150:151], v[86:87], v[62:63] op_sel:[0,1,0]
	v_pk_fma_f32 v[2:3], v[148:149], v[88:89], v[2:3] op_sel:[0,1,0]
	v_pk_fma_f32 v[60:61], v[150:151], v[88:89], v[60:61] op_sel:[0,1,0]
	v_pk_fma_f32 v[58:59], v[148:149], v[90:91], v[58:59] op_sel:[0,1,0]
	v_pk_fma_f32 v[56:57], v[150:151], v[90:91], v[56:57] op_sel:[0,1,0]
	v_pk_fma_f32 v[0:1], v[148:149], v[92:93], v[0:1] op_sel:[0,1,0]
	v_pk_fma_f32 v[50:51], v[150:151], v[92:93], v[50:51] op_sel:[0,1,0]
	v_pk_fma_f32 v[46:47], v[148:149], v[94:95], v[46:47] op_sel:[0,1,0]
	v_pk_fma_f32 v[42:43], v[150:151], v[94:95], v[42:43] op_sel:[0,1,0]
	v_pk_fma_f32 v[6:7], v[148:149], v[96:97], v[6:7] op_sel:[0,1,0]
	v_pk_fma_f32 v[40:41], v[150:151], v[96:97], v[40:41] op_sel:[0,1,0]
	v_pk_fma_f32 v[38:39], v[148:149], v[98:99], v[38:39] op_sel:[0,1,0]
	v_pk_fma_f32 v[36:37], v[150:151], v[98:99], v[36:37] op_sel:[0,1,0]
	v_pk_fma_f32 v[4:5], v[148:149], v[100:101], v[4:5] op_sel:[0,1,0]
	v_pk_fma_f32 v[34:35], v[150:151], v[100:101], v[34:35] op_sel:[0,1,0]
	v_pk_fma_f32 v[32:33], v[148:149], v[102:103], v[32:33] op_sel:[0,1,0]
	v_pk_fma_f32 v[30:31], v[150:151], v[102:103], v[30:31] op_sel:[0,1,0]
	v_pk_fma_f32 v[10:11], v[148:149], v[104:105], v[10:11] op_sel:[0,1,0]
	v_pk_fma_f32 v[28:29], v[150:151], v[104:105], v[28:29] op_sel:[0,1,0]
	v_pk_fma_f32 v[26:27], v[148:149], v[106:107], v[26:27] op_sel:[0,1,0]
	v_pk_fma_f32 v[24:25], v[150:151], v[106:107], v[24:25] op_sel:[0,1,0]
	v_pk_fma_f32 v[8:9], v[148:149], v[108:109], v[8:9] op_sel:[0,1,0]
	v_pk_fma_f32 v[22:23], v[150:151], v[108:109], v[22:23] op_sel:[0,1,0]
	v_pk_fma_f32 v[20:21], v[148:149], v[110:111], v[20:21] op_sel:[0,1,0]
	v_pk_fma_f32 v[18:19], v[150:151], v[110:111], v[18:19] op_sel:[0,1,0]
	s_add_u32 s100, s0, 0x8000
	s_min_u32 s100, s100, 0x3e000
	v_lshl_add_u64 v[176:177], v[44:45], 0, s[100:101]
	global_load_dword v145, v[176:177], off
	global_load_dword v144, v[176:177], off offset:1024
	global_load_dword v147, v[176:177], off offset:2048
	global_load_dword v146, v[176:177], off offset:3072
	v_add_co_u32_e32 v178, vcc, 0x1000, v176
	v_addc_co_u32_e32 v179, vcc, 0, v177, vcc
	global_load_dword v149, v[178:179], off
	global_load_dword v148, v[178:179], off offset:1024
	global_load_dword v151, v[178:179], off offset:2048
	global_load_dword v150, v[178:179], off offset:3072
	s_add_u32 s0, s0, 0x2000
	s_addc_u32 s1, s1, 0
	v_mov_b32_e32 v12, s36
	ds_read2_b64 v[80:83], v12 offset1:32
	ds_read2_b64 v[84:87], v12 offset0:64 offset1:96
	ds_read2_b64 v[88:91], v12 offset0:128 offset1:160
	ds_read2_b64 v[92:95], v12 offset0:192 offset1:224
	v_add_u32_e32 v12, 0x800, v12
	ds_read2_b64 v[96:99], v12 offset1:32
	ds_read2_b64 v[100:103], v12 offset0:64 offset1:96
	ds_read2_b64 v[104:107], v12 offset0:128 offset1:160
	ds_read2_b64 v[108:111], v12 offset0:192 offset1:224
	s_add_i32 s36, s36, 8
	s_waitcnt vmcnt(24) lgkmcnt(7)
	v_pk_fma_f32 v[72:73], v[152:153], v[80:81], v[72:73] op_sel_hi:[1,0,1]
	v_pk_fma_f32 v[68:69], v[152:153], v[82:83], v[68:69] op_sel_hi:[1,0,1]
	v_pk_fma_f32 v[70:71], v[154:155], v[80:81], v[70:71] op_sel_hi:[1,0,1]
	v_pk_fma_f32 v[52:53], v[154:155], v[82:83], v[52:53] op_sel_hi:[1,0,1]
	s_waitcnt lgkmcnt(6)
	v_pk_fma_f32 v[54:55], v[152:153], v[84:85], v[54:55] op_sel_hi:[1,0,1]
	v_pk_fma_f32 v[66:67], v[154:155], v[84:85], v[66:67] op_sel_hi:[1,0,1]
	v_pk_fma_f32 v[64:65], v[152:153], v[86:87], v[64:65] op_sel_hi:[1,0,1]
	v_pk_fma_f32 v[62:63], v[154:155], v[86:87], v[62:63] op_sel_hi:[1,0,1]
	s_waitcnt lgkmcnt(5)
	v_pk_fma_f32 v[2:3], v[152:153], v[88:89], v[2:3] op_sel_hi:[1,0,1]
	v_pk_fma_f32 v[60:61], v[154:155], v[88:89], v[60:61] op_sel_hi:[1,0,1]
	v_pk_fma_f32 v[58:59], v[152:153], v[90:91], v[58:59] op_sel_hi:[1,0,1]
	v_pk_fma_f32 v[56:57], v[154:155], v[90:91], v[56:57] op_sel_hi:[1,0,1]
	s_waitcnt lgkmcnt(4)
; DI void filter_item(const Params& p, int layer, int L, int tile, char* smem) {
;     ...
;   for (int e = 0; e < 64; ++e) {
;     const float* wr = w3 + e * 1024 + ch;
;     const float w0 = wr[0], w1v = wr[256], w2v = wr[512], w3v = wr[768];
; #pragma unroll
;     for (int ml = 0; ml < 16; ++ml) {
;       const float hv = h2[ml * 64 + e];
;       fa[ml][0] += hv * w0; fa[ml][1] += hv * w1v; fa[ml][2] += hv * w2v; fa[ml][3] += hv * w3v;
;     }
;   }
	v_pk_fma_f32 v[0:1], v[152:153], v[92:93], v[0:1] op_sel_hi:[1,0,1]
	v_pk_fma_f32 v[50:51], v[154:155], v[92:93], v[50:51] op_sel_hi:[1,0,1]
	v_pk_fma_f32 v[46:47], v[152:153], v[94:95], v[46:47] op_sel_hi:[1,0,1]
	v_pk_fma_f32 v[42:43], v[154:155], v[94:95], v[42:43] op_sel_hi:[1,0,1]
	s_waitcnt lgkmcnt(3)
	v_pk_fma_f32 v[6:7], v[152:153], v[96:97], v[6:7] op_sel_hi:[1,0,1]
	v_pk_fma_f32 v[40:41], v[154:155], v[96:97], v[40:41] op_sel_hi:[1,0,1]
	v_pk_fma_f32 v[38:39], v[152:153], v[98:99], v[38:39] op_sel_hi:[1,0,1]
	v_pk_fma_f32 v[36:37], v[154:155], v[98:99], v[36:37] op_sel_hi:[1,0,1]
	s_waitcnt lgkmcnt(2)
	v_pk_fma_f32 v[4:5], v[152:153], v[100:101], v[4:5] op_sel_hi:[1,0,1]
	v_pk_fma_f32 v[34:35], v[154:155], v[100:101], v[34:35] op_sel_hi:[1,0,1]
	v_pk_fma_f32 v[32:33], v[152:153], v[102:103], v[32:33] op_sel_hi:[1,0,1]
	v_pk_fma_f32 v[30:31], v[154:155], v[102:103], v[30:31] op_sel_hi:[1,0,1]
	s_waitcnt lgkmcnt(1)
	v_pk_fma_f32 v[10:11], v[152:153], v[104:105], v[10:11] op_sel_hi:[1,0,1]
	v_pk_fma_f32 v[28:29], v[154:155], v[104:105], v[28:29] op_sel_hi:[1,0,1]
	v_pk_fma_f32 v[26:27], v[152:153], v[106:107], v[26:27] op_sel_hi:[1,0,1]
	v_pk_fma_f32 v[24:25], v[154:155], v[106:107], v[24:25] op_sel_hi:[1,0,1]
	s_waitcnt lgkmcnt(0)
	v_pk_fma_f32 v[8:9], v[152:153], v[108:109], v[8:9] op_sel_hi:[1,0,1]
	v_pk_fma_f32 v[22:23], v[154:155], v[108:109], v[22:23] op_sel_hi:[1,0,1]
	v_pk_fma_f32 v[20:21], v[152:153], v[110:111], v[20:21] op_sel_hi:[1,0,1]
	v_pk_fma_f32 v[18:19], v[154:155], v[110:111], v[18:19] op_sel_hi:[1,0,1]
	v_pk_fma_f32 v[72:73], v[156:157], v[80:81], v[72:73] op_sel:[0,1,0]
	v_pk_fma_f32 v[68:69], v[156:157], v[82:83], v[68:69] op_sel:[0,1,0]
	v_pk_fma_f32 v[70:71], v[158:159], v[80:81], v[70:71] op_sel:[0,1,0]
	v_pk_fma_f32 v[52:53], v[158:159], v[82:83], v[52:53] op_sel:[0,1,0]
	v_pk_fma_f32 v[54:55], v[156:157], v[84:85], v[54:55] op_sel:[0,1,0]
	v_pk_fma_f32 v[66:67], v[158:159], v[84:85], v[66:67] op_sel:[0,1,0]
	v_pk_fma_f32 v[64:65], v[156:157], v[86:87], v[64:65] op_sel:[0,1,0]
	v_pk_fma_f32 v[62:63], v[158:159], v[86:87], v[62:63] op_sel:[0,1,0]
	v_pk_fma_f32 v[2:3], v[156:157], v[88:89], v[2:3] op_sel:[0,1,0]
	v_pk_fma_f32 v[60:61], v[158:159], v[88:89], v[60:61] op_sel:[0,1,0]
	v_pk_fma_f32 v[58:59], v[156:157], v[90:91], v[58:59] op_sel:[0,1,0]
	v_pk_fma_f32 v[56:57], v[158:159], v[90:91], v[56:57] op_sel:[0,1,0]
	v_pk_fma_f32 v[0:1], v[156:157], v[92:93], v[0:1] op_sel:[0,1,0]
	v_pk_fma_f32 v[50:51], v[158:159], v[92:93], v[50:51] op_sel:[0,1,0]
	v_pk_fma_f32 v[46:47], v[156:157], v[94:95], v[46:47] op_sel:[0,1,0]
	v_pk_fma_f32 v[42:43], v[158:159], v[94:95], v[42:43] op_sel:[0,1,0]
	v_pk_fma_f32 v[6:7], v[156:157], v[96:97], v[6:7] op_sel:[0,1,0]
	v_pk_fma_f32 v[40:41], v[158:159], v[96:97], v[40:41] op_sel:[0,1,0]
	v_pk_fma_f32 v[38:39], v[156:157], v[98:99], v[38:39] op_sel:[0,1,0]
	v_pk_fma_f32 v[36:37], v[158:159], v[98:99], v[36:37] op_sel:[0,1,0]
	v_pk_fma_f32 v[4:5], v[156:157], v[100:101], v[4:5] op_sel:[0,1,0]
	v_pk_fma_f32 v[34:35], v[158:159], v[100:101], v[34:35] op_sel:[0,1,0]
	v_pk_fma_f32 v[32:33], v[156:157], v[102:103], v[32:33] op_sel:[0,1,0]
	v_pk_fma_f32 v[30:31], v[158:159], v[102:103], v[30:31] op_sel:[0,1,0]
	v_pk_fma_f32 v[10:11], v[156:157], v[104:105], v[10:11] op_sel:[0,1,0]
	v_pk_fma_f32 v[28:29], v[158:159], v[104:105], v[28:29] op_sel:[0,1,0]
	v_pk_fma_f32 v[26:27], v[156:157], v[106:107], v[26:27] op_sel:[0,1,0]
	v_pk_fma_f32 v[24:25], v[158:159], v[106:107], v[24:25] op_sel:[0,1,0]
	v_pk_fma_f32 v[8:9], v[156:157], v[108:109], v[8:9] op_sel:[0,1,0]
	v_pk_fma_f32 v[22:23], v[158:159], v[108:109], v[22:23] op_sel:[0,1,0]
	v_pk_fma_f32 v[20:21], v[156:157], v[110:111], v[20:21] op_sel:[0,1,0]
	v_pk_fma_f32 v[18:19], v[158:159], v[110:111], v[18:19] op_sel:[0,1,0]
	s_add_u32 s100, s0, 0x8000
	s_min_u32 s100, s100, 0x3e000
	v_lshl_add_u64 v[176:177], v[44:45], 0, s[100:101]
	global_load_dword v153, v[176:177], off
	global_load_dword v152, v[176:177], off offset:1024
	global_load_dword v155, v[176:177], off offset:2048
	global_load_dword v154, v[176:177], off offset:3072
	v_add_co_u32_e32 v178, vcc, 0x1000, v176
	v_addc_co_u32_e32 v179, vcc, 0, v177, vcc
	global_load_dword v157, v[178:179], off
	global_load_dword v156, v[178:179], off offset:1024
	global_load_dword v159, v[178:179], off offset:2048
	global_load_dword v158, v[178:179], off offset:3072
	s_add_u32 s0, s0, 0x2000
	s_addc_u32 s1, s1, 0
	v_mov_b32_e32 v12, s36
	ds_read2_b64 v[80:83], v12 offset1:32
	ds_read2_b64 v[84:87], v12 offset0:64 offset1:96
	ds_read2_b64 v[88:91], v12 offset0:128 offset1:160
	ds_read2_b64 v[92:95], v12 offset0:192 offset1:224
	v_add_u32_e32 v12, 0x800, v12
	ds_read2_b64 v[96:99], v12 offset1:32
	ds_read2_b64 v[100:103], v12 offset0:64 offset1:96
	ds_read2_b64 v[104:107], v12 offset0:128 offset1:160
	ds_read2_b64 v[108:111], v12 offset0:192 offset1:224
	s_add_i32 s36, s36, 8
	s_waitcnt vmcnt(24) lgkmcnt(7)
	v_pk_fma_f32 v[72:73], v[160:161], v[80:81], v[72:73] op_sel_hi:[1,0,1]
	v_pk_fma_f32 v[68:69], v[160:161], v[82:83], v[68:69] op_sel_hi:[1,0,1]
	v_pk_fma_f32 v[70:71], v[162:163], v[80:81], v[70:71] op_sel_hi:[1,0,1]
	v_pk_fma_f32 v[52:53], v[162:163], v[82:83], v[52:53] op_sel_hi:[1,0,1]
	s_waitcnt lgkmcnt(6)
	v_pk_fma_f32 v[54:55], v[160:161], v[84:85], v[54:55] op_sel_hi:[1,0,1]
	v_pk_fma_f32 v[66:67], v[162:163], v[84:85], v[66:67] op_sel_hi:[1,0,1]
	v_pk_fma_f32 v[64:65], v[160:161], v[86:87], v[64:65] op_sel_hi:[1,0,1]
	v_pk_fma_f32 v[62:63], v[162:163], v[86:87], v[62:63] op_sel_hi:[1,0,1]
	s_waitcnt lgkmcnt(5)
; DI void filter_item(const Params& p, int layer, int L, int tile, char* smem) {
;     ...
;   for (int e = 0; e < 64; ++e) {
;     const float* wr = w3 + e * 1024 + ch;
;     const float w0 = wr[0], w1v = wr[256], w2v = wr[512], w3v = wr[768];
; #pragma unroll
;     for (int ml = 0; ml < 16; ++ml) {
;       const float hv = h2[ml * 64 + e];
;       fa[ml][0] += hv * w0; fa[ml][1] += hv * w1v; fa[ml][2] += hv * w2v; fa[ml][3] += hv * w3v;
;     }
;   }
	v_pk_fma_f32 v[2:3], v[160:161], v[88:89], v[2:3] op_sel_hi:[1,0,1]
	v_pk_fma_f32 v[60:61], v[162:163], v[88:89], v[60:61] op_sel_hi:[1,0,1]
	v_pk_fma_f32 v[58:59], v[160:161], v[90:91], v[58:59] op_sel_hi:[1,0,1]
	v_pk_fma_f32 v[56:57], v[162:163], v[90:91], v[56:57] op_sel_hi:[1,0,1]
	s_waitcnt lgkmcnt(4)
	v_pk_fma_f32 v[0:1], v[160:161], v[92:93], v[0:1] op_sel_hi:[1,0,1]
	v_pk_fma_f32 v[50:51], v[162:163], v[92:93], v[50:51] op_sel_hi:[1,0,1]
	v_pk_fma_f32 v[46:47], v[160:161], v[94:95], v[46:47] op_sel_hi:[1,0,1]
	v_pk_fma_f32 v[42:43], v[162:163], v[94:95], v[42:43] op_sel_hi:[1,0,1]
	s_waitcnt lgkmcnt(3)
	v_pk_fma_f32 v[6:7], v[160:161], v[96:97], v[6:7] op_sel_hi:[1,0,1]
	v_pk_fma_f32 v[40:41], v[162:163], v[96:97], v[40:41] op_sel_hi:[1,0,1]
	v_pk_fma_f32 v[38:39], v[160:161], v[98:99], v[38:39] op_sel_hi:[1,0,1]
	v_pk_fma_f32 v[36:37], v[162:163], v[98:99], v[36:37] op_sel_hi:[1,0,1]
	s_waitcnt lgkmcnt(2)
	v_pk_fma_f32 v[4:5], v[160:161], v[100:101], v[4:5] op_sel_hi:[1,0,1]
	v_pk_fma_f32 v[34:35], v[162:163], v[100:101], v[34:35] op_sel_hi:[1,0,1]
	v_pk_fma_f32 v[32:33], v[160:161], v[102:103], v[32:33] op_sel_hi:[1,0,1]
	v_pk_fma_f32 v[30:31], v[162:163], v[102:103], v[30:31] op_sel_hi:[1,0,1]
	s_waitcnt lgkmcnt(1)
	v_pk_fma_f32 v[10:11], v[160:161], v[104:105], v[10:11] op_sel_hi:[1,0,1]
	v_pk_fma_f32 v[28:29], v[162:163], v[104:105], v[28:29] op_sel_hi:[1,0,1]
	v_pk_fma_f32 v[26:27], v[160:161], v[106:107], v[26:27] op_sel_hi:[1,0,1]
	v_pk_fma_f32 v[24:25], v[162:163], v[106:107], v[24:25] op_sel_hi:[1,0,1]
	s_waitcnt lgkmcnt(0)
	v_pk_fma_f32 v[8:9], v[160:161], v[108:109], v[8:9] op_sel_hi:[1,0,1]
	v_pk_fma_f32 v[22:23], v[162:163], v[108:109], v[22:23] op_sel_hi:[1,0,1]
	v_pk_fma_f32 v[20:21], v[160:161], v[110:111], v[20:21] op_sel_hi:[1,0,1]
	v_pk_fma_f32 v[18:19], v[162:163], v[110:111], v[18:19] op_sel_hi:[1,0,1]
	v_pk_fma_f32 v[72:73], v[164:165], v[80:81], v[72:73] op_sel:[0,1,0]
	v_pk_fma_f32 v[68:69], v[164:165], v[82:83], v[68:69] op_sel:[0,1,0]
	v_pk_fma_f32 v[70:71], v[166:167], v[80:81], v[70:71] op_sel:[0,1,0]
	v_pk_fma_f32 v[52:53], v[166:167], v[82:83], v[52:53] op_sel:[0,1,0]
	v_pk_fma_f32 v[54:55], v[164:165], v[84:85], v[54:55] op_sel:[0,1,0]
	v_pk_fma_f32 v[66:67], v[166:167], v[84:85], v[66:67] op_sel:[0,1,0]
	v_pk_fma_f32 v[64:65], v[164:165], v[86:87], v[64:65] op_sel:[0,1,0]
	v_pk_fma_f32 v[62:63], v[166:167], v[86:87], v[62:63] op_sel:[0,1,0]
	v_pk_fma_f32 v[2:3], v[164:165], v[88:89], v[2:3] op_sel:[0,1,0]
	v_pk_fma_f32 v[60:61], v[166:167], v[88:89], v[60:61] op_sel:[0,1,0]
	v_pk_fma_f32 v[58:59], v[164:165], v[90:91], v[58:59] op_sel:[0,1,0]
	v_pk_fma_f32 v[56:57], v[166:167], v[90:91], v[56:57] op_sel:[0,1,0]
	v_pk_fma_f32 v[0:1], v[164:165], v[92:93], v[0:1] op_sel:[0,1,0]
	v_pk_fma_f32 v[50:51], v[166:167], v[92:93], v[50:51] op_sel:[0,1,0]
	v_pk_fma_f32 v[46:47], v[164:165], v[94:95], v[46:47] op_sel:[0,1,0]
	v_pk_fma_f32 v[42:43], v[166:167], v[94:95], v[42:43] op_sel:[0,1,0]
	v_pk_fma_f32 v[6:7], v[164:165], v[96:97], v[6:7] op_sel:[0,1,0]
	v_pk_fma_f32 v[40:41], v[166:167], v[96:97], v[40:41] op_sel:[0,1,0]
	v_pk_fma_f32 v[38:39], v[164:165], v[98:99], v[38:39] op_sel:[0,1,0]
	v_pk_fma_f32 v[36:37], v[166:167], v[98:99], v[36:37] op_sel:[0,1,0]
	v_pk_fma_f32 v[4:5], v[164:165], v[100:101], v[4:5] op_sel:[0,1,0]
	v_pk_fma_f32 v[34:35], v[166:167], v[100:101], v[34:35] op_sel:[0,1,0]
	v_pk_fma_f32 v[32:33], v[164:165], v[102:103], v[32:33] op_sel:[0,1,0]
	v_pk_fma_f32 v[30:31], v[166:167], v[102:103], v[30:31] op_sel:[0,1,0]
	v_pk_fma_f32 v[10:11], v[164:165], v[104:105], v[10:11] op_sel:[0,1,0]
	v_pk_fma_f32 v[28:29], v[166:167], v[104:105], v[28:29] op_sel:[0,1,0]
	v_pk_fma_f32 v[26:27], v[164:165], v[106:107], v[26:27] op_sel:[0,1,0]
	v_pk_fma_f32 v[24:25], v[166:167], v[106:107], v[24:25] op_sel:[0,1,0]
	v_pk_fma_f32 v[8:9], v[164:165], v[108:109], v[8:9] op_sel:[0,1,0]
	v_pk_fma_f32 v[22:23], v[166:167], v[108:109], v[22:23] op_sel:[0,1,0]
	v_pk_fma_f32 v[20:21], v[164:165], v[110:111], v[20:21] op_sel:[0,1,0]
	v_pk_fma_f32 v[18:19], v[166:167], v[110:111], v[18:19] op_sel:[0,1,0]
	s_add_u32 s100, s0, 0x8000
	s_min_u32 s100, s100, 0x3e000
	v_lshl_add_u64 v[176:177], v[44:45], 0, s[100:101]
	global_load_dword v161, v[176:177], off
	global_load_dword v160, v[176:177], off offset:1024
	global_load_dword v163, v[176:177], off offset:2048
	global_load_dword v162, v[176:177], off offset:3072
	v_add_co_u32_e32 v178, vcc, 0x1000, v176
	v_addc_co_u32_e32 v179, vcc, 0, v177, vcc
	global_load_dword v165, v[178:179], off
	global_load_dword v164, v[178:179], off offset:1024
	global_load_dword v167, v[178:179], off offset:2048
	global_load_dword v166, v[178:179], off offset:3072
	s_add_u32 s0, s0, 0x2000
	s_addc_u32 s1, s1, 0
	v_mov_b32_e32 v12, s36
	ds_read2_b64 v[80:83], v12 offset1:32
	ds_read2_b64 v[84:87], v12 offset0:64 offset1:96
	ds_read2_b64 v[88:91], v12 offset0:128 offset1:160
	ds_read2_b64 v[92:95], v12 offset0:192 offset1:224
	v_add_u32_e32 v12, 0x800, v12
	ds_read2_b64 v[96:99], v12 offset1:32
	ds_read2_b64 v[100:103], v12 offset0:64 offset1:96
	ds_read2_b64 v[104:107], v12 offset0:128 offset1:160
	ds_read2_b64 v[108:111], v12 offset0:192 offset1:224
	s_add_i32 s36, s36, 8
	s_waitcnt vmcnt(24) lgkmcnt(7)
	v_pk_fma_f32 v[72:73], v[168:169], v[80:81], v[72:73] op_sel_hi:[1,0,1]
	v_pk_fma_f32 v[68:69], v[168:169], v[82:83], v[68:69] op_sel_hi:[1,0,1]
	v_pk_fma_f32 v[70:71], v[170:171], v[80:81], v[70:71] op_sel_hi:[1,0,1]
	v_pk_fma_f32 v[52:53], v[170:171], v[82:83], v[52:53] op_sel_hi:[1,0,1]
	s_waitcnt lgkmcnt(6)
; DI bf16_t f2bf(float x) { return (bf16_t)(pack2(x, x) & 0xffffu); }
; DI void filter_item(const Params& p, int layer, int L, int tile, char* smem) {
;     ...
;   for (int e = 0; e < 64; ++e) {
;     const float* wr = w3 + e * 1024 + ch;
;     const float w0 = wr[0], w1v = wr[256], w2v = wr[512], w3v = wr[768];
; #pragma unroll
;     for (int ml = 0; ml < 16; ++ml) {
;       const float hv = h2[ml * 64 + e];
;       fa[ml][0] += hv * w0; fa[ml][1] += hv * w1v; fa[ml][2] += hv * w2v; fa[ml][3] += hv * w3v;
;     }
;   }
; #pragma unroll
;   for (int ml = 0; ml < 16; ++ml) {
;     float a00 = fa[ml][0], a01 = fa[ml][1], a10 = fa[ml][2], a11 = fa[ml][3];
;     const int m = m0 + ml;
;     const float t = (float)m / (float)(L - 1);
;     const float dec = __expf(-t * delta);
;     a00 *= dec; a01 *= dec; a10 *= dec; a11 *= dec;
;     ps0 += fabsf(a00); ps1 += fabsf(a10);
;     if (m > 0) { ps0 += fabsf(a01); ps1 += fabsf(a11); }
;     if (L == SEQ) {
;       bf16_t* k0 = (bf16_t*)(p.ws + OFF_KREV) + ((size_t)(layer * 2 + 0) * 256 + ch) * 8192;
;       bf16_t* k1 = (bf16_t*)(p.ws + OFF_KREV) + ((size_t)(layer * 2 + 1) * 256 + ch) * 8192;
;       k0[L - 1 - m] = f2bf(a00); k1[L - 1 - m] = f2bf(a10);
;       if (m > 0) { k0[L - 1 + m] = f2bf(a01); k1[L - 1 + m] = f2bf(a11); }
;       else { k0[2 * L - 1] = 0; k1[2 * L - 1] = 0; }
;     } else {
;       float* k0 = (float*)(p.ws + OFF_KREVC) + ((size_t)0 * 256 + ch) * 512;
;       float* k1 = (float*)(p.ws + OFF_KREVC) + ((size_t)1 * 256 + ch) * 512;
;       k0[L - 1 - m] = a00; k1[L - 1 - m] = a10;
;       if (m > 0) { k0[L - 1 + m] = a01; k1[L - 1 + m] = a11; }
;       else { k0[2 * L - 1] = 0.f; k1[2 * L - 1] = 0.f; }
	v_pk_fma_f32 v[54:55], v[168:169], v[84:85], v[54:55] op_sel_hi:[1,0,1]
	v_pk_fma_f32 v[66:67], v[170:171], v[84:85], v[66:67] op_sel_hi:[1,0,1]
	v_pk_fma_f32 v[64:65], v[168:169], v[86:87], v[64:65] op_sel_hi:[1,0,1]
	v_pk_fma_f32 v[62:63], v[170:171], v[86:87], v[62:63] op_sel_hi:[1,0,1]
	s_waitcnt lgkmcnt(5)
	v_pk_fma_f32 v[2:3], v[168:169], v[88:89], v[2:3] op_sel_hi:[1,0,1]
	v_pk_fma_f32 v[60:61], v[170:171], v[88:89], v[60:61] op_sel_hi:[1,0,1]
	v_pk_fma_f32 v[58:59], v[168:169], v[90:91], v[58:59] op_sel_hi:[1,0,1]
	v_pk_fma_f32 v[56:57], v[170:171], v[90:91], v[56:57] op_sel_hi:[1,0,1]
	s_waitcnt lgkmcnt(4)
	v_pk_fma_f32 v[0:1], v[168:169], v[92:93], v[0:1] op_sel_hi:[1,0,1]
	v_pk_fma_f32 v[50:51], v[170:171], v[92:93], v[50:51] op_sel_hi:[1,0,1]
	v_pk_fma_f32 v[46:47], v[168:169], v[94:95], v[46:47] op_sel_hi:[1,0,1]
	v_pk_fma_f32 v[42:43], v[170:171], v[94:95], v[42:43] op_sel_hi:[1,0,1]
	s_waitcnt lgkmcnt(3)
	v_pk_fma_f32 v[6:7], v[168:169], v[96:97], v[6:7] op_sel_hi:[1,0,1]
	v_pk_fma_f32 v[40:41], v[170:171], v[96:97], v[40:41] op_sel_hi:[1,0,1]
	v_pk_fma_f32 v[38:39], v[168:169], v[98:99], v[38:39] op_sel_hi:[1,0,1]
	v_pk_fma_f32 v[36:37], v[170:171], v[98:99], v[36:37] op_sel_hi:[1,0,1]
	s_waitcnt lgkmcnt(2)
	v_pk_fma_f32 v[4:5], v[168:169], v[100:101], v[4:5] op_sel_hi:[1,0,1]
	v_pk_fma_f32 v[34:35], v[170:171], v[100:101], v[34:35] op_sel_hi:[1,0,1]
	v_pk_fma_f32 v[32:33], v[168:169], v[102:103], v[32:33] op_sel_hi:[1,0,1]
	v_pk_fma_f32 v[30:31], v[170:171], v[102:103], v[30:31] op_sel_hi:[1,0,1]
	s_waitcnt lgkmcnt(1)
	v_pk_fma_f32 v[10:11], v[168:169], v[104:105], v[10:11] op_sel_hi:[1,0,1]
	v_pk_fma_f32 v[28:29], v[170:171], v[104:105], v[28:29] op_sel_hi:[1,0,1]
	v_pk_fma_f32 v[26:27], v[168:169], v[106:107], v[26:27] op_sel_hi:[1,0,1]
	v_pk_fma_f32 v[24:25], v[170:171], v[106:107], v[24:25] op_sel_hi:[1,0,1]
	s_waitcnt lgkmcnt(0)
	v_pk_fma_f32 v[8:9], v[168:169], v[108:109], v[8:9] op_sel_hi:[1,0,1]
	v_pk_fma_f32 v[22:23], v[170:171], v[108:109], v[22:23] op_sel_hi:[1,0,1]
	v_pk_fma_f32 v[20:21], v[168:169], v[110:111], v[20:21] op_sel_hi:[1,0,1]
	v_pk_fma_f32 v[18:19], v[170:171], v[110:111], v[18:19] op_sel_hi:[1,0,1]
	v_pk_fma_f32 v[72:73], v[172:173], v[80:81], v[72:73] op_sel:[0,1,0]
	v_pk_fma_f32 v[68:69], v[172:173], v[82:83], v[68:69] op_sel:[0,1,0]
	v_pk_fma_f32 v[70:71], v[174:175], v[80:81], v[70:71] op_sel:[0,1,0]
	v_pk_fma_f32 v[52:53], v[174:175], v[82:83], v[52:53] op_sel:[0,1,0]
	v_pk_fma_f32 v[54:55], v[172:173], v[84:85], v[54:55] op_sel:[0,1,0]
	v_pk_fma_f32 v[66:67], v[174:175], v[84:85], v[66:67] op_sel:[0,1,0]
	v_pk_fma_f32 v[64:65], v[172:173], v[86:87], v[64:65] op_sel:[0,1,0]
	v_pk_fma_f32 v[62:63], v[174:175], v[86:87], v[62:63] op_sel:[0,1,0]
	v_pk_fma_f32 v[2:3], v[172:173], v[88:89], v[2:3] op_sel:[0,1,0]
	v_pk_fma_f32 v[60:61], v[174:175], v[88:89], v[60:61] op_sel:[0,1,0]
	v_pk_fma_f32 v[58:59], v[172:173], v[90:91], v[58:59] op_sel:[0,1,0]
	v_pk_fma_f32 v[56:57], v[174:175], v[90:91], v[56:57] op_sel:[0,1,0]
	v_pk_fma_f32 v[0:1], v[172:173], v[92:93], v[0:1] op_sel:[0,1,0]
	v_pk_fma_f32 v[50:51], v[174:175], v[92:93], v[50:51] op_sel:[0,1,0]
	v_pk_fma_f32 v[46:47], v[172:173], v[94:95], v[46:47] op_sel:[0,1,0]
	v_pk_fma_f32 v[42:43], v[174:175], v[94:95], v[42:43] op_sel:[0,1,0]
	v_pk_fma_f32 v[6:7], v[172:173], v[96:97], v[6:7] op_sel:[0,1,0]
	v_pk_fma_f32 v[40:41], v[174:175], v[96:97], v[40:41] op_sel:[0,1,0]
	v_pk_fma_f32 v[38:39], v[172:173], v[98:99], v[38:39] op_sel:[0,1,0]
	v_pk_fma_f32 v[36:37], v[174:175], v[98:99], v[36:37] op_sel:[0,1,0]
	v_pk_fma_f32 v[4:5], v[172:173], v[100:101], v[4:5] op_sel:[0,1,0]
	v_pk_fma_f32 v[34:35], v[174:175], v[100:101], v[34:35] op_sel:[0,1,0]
	v_pk_fma_f32 v[32:33], v[172:173], v[102:103], v[32:33] op_sel:[0,1,0]
	v_pk_fma_f32 v[30:31], v[174:175], v[102:103], v[30:31] op_sel:[0,1,0]
	v_pk_fma_f32 v[10:11], v[172:173], v[104:105], v[10:11] op_sel:[0,1,0]
	v_pk_fma_f32 v[28:29], v[174:175], v[104:105], v[28:29] op_sel:[0,1,0]
	v_pk_fma_f32 v[26:27], v[172:173], v[106:107], v[26:27] op_sel:[0,1,0]
	v_pk_fma_f32 v[24:25], v[174:175], v[106:107], v[24:25] op_sel:[0,1,0]
	v_pk_fma_f32 v[8:9], v[172:173], v[108:109], v[8:9] op_sel:[0,1,0]
	v_pk_fma_f32 v[22:23], v[174:175], v[108:109], v[22:23] op_sel:[0,1,0]
	v_pk_fma_f32 v[20:21], v[172:173], v[110:111], v[20:21] op_sel:[0,1,0]
	v_pk_fma_f32 v[18:19], v[174:175], v[110:111], v[18:19] op_sel:[0,1,0]
	s_add_u32 s100, s0, 0x8000
	s_min_u32 s100, s100, 0x3e000
	v_lshl_add_u64 v[176:177], v[44:45], 0, s[100:101]
	global_load_dword v169, v[176:177], off
	global_load_dword v168, v[176:177], off offset:1024
	global_load_dword v171, v[176:177], off offset:2048
	global_load_dword v170, v[176:177], off offset:3072
	v_add_co_u32_e32 v178, vcc, 0x1000, v176
	v_addc_co_u32_e32 v179, vcc, 0, v177, vcc
	global_load_dword v173, v[178:179], off
	global_load_dword v172, v[178:179], off offset:1024
	global_load_dword v175, v[178:179], off offset:2048
	global_load_dword v174, v[178:179], off offset:3072
	s_add_u32 s0, s0, 0x2000
	s_addc_u32 s1, s1, 0
	s_cmp_eq_u32 s0, 0x40000
	s_cbranch_scc0 .LBB0_127
	v_cvt_f32_u32_e32 v12, s14
	v_cvt_f32_i32_e32 v44, v16
	s_cmp_eq_u32 s56, 0
	s_mov_b32 s37, s15
	v_div_scale_f32 v45, s[0:1], s90, s90, v12
	v_rcp_f32_e32 v48, v45
	v_fmamk_f32 v79, v44, 0x3d4541ff, v74
	v_div_scale_f32 v44, vcc, v12, s90, v12
	v_fma_f32 v49, -v45, v48, 1.0
	v_fmac_f32_e32 v48, v49, v48
	v_mul_f32_e32 v49, v44, v48
	v_fma_f32 v80, -v45, v49, v44
	v_fmac_f32_e32 v49, v80, v48
	v_fma_f32 v44, -v45, v49, v44
	v_div_fmas_f32 v44, v44, v48, v49
	v_div_fixup_f32 v12, v44, s90, v12
	v_mul_f32_e64 v12, v12, |v79|
	v_mul_f32_e32 v12, 0x3fb8aa3b, v12
	v_exp_f32_e32 v80, v12
	v_lshlrev_b64 v[44:45], 11, v[16:17]
	v_lshl_add_u64 v[48:49], s[4:5], 0, v[44:45]
	s_mov_b64 s[0:1], 0x80000
	v_lshl_add_u64 v[44:45], v[48:49], 0, s[0:1]
	s_cselect_b64 s[0:1], -1, 0
	s_sub_i32 s36, 0xff, s14
	s_lshl_b32 s36, s36, 2
	v_mul_f32_e32 v12, v80, v73
	v_mul_f32_e32 v72, v80, v72
	v_mul_f32_e32 v71, v80, v71
	v_mul_f32_e32 v70, v80, v70
	v_lshl_add_u64 v[80:81], v[48:49], 0, s[36:37]
	s_cmp_lg_u32 s56, 0
	global_store_dword v[80:81], v12, off
	v_lshl_add_u64 v[80:81], v[44:45], 0, s[36:37]
	global_store_dword v[80:81], v71, off
	s_cbranch_scc0 .LBB0_130
	s_add_i32 s36, s14, 0xff
	s_mov_b32 s37, s15
	v_lshl_add_u64 v[80:81], s[14:15], 2, v[48:49]
	global_store_dword v[80:81], v72, off offset:1020
	v_lshl_add_u64 v[80:81], s[36:37], 2, v[44:45]
	global_store_dword v[80:81], v70, off
	s_cbranch_execz .LBB0_131
	s_branch .LBB0_132

; DI void phase_mix_a(const Params& p, int layer, char* smem) {
;     ...
;   const int MT = NTOK / 128;
;   gemm_phase<EPI_QUP>(p, layer, (const bf16_t*)(p.ws + OFF_MQN), 256, wl + W_UQ, 256, 256, (layer == 0) ? MT : NLAT / 128, 5, smem);
.LBB0_599:
	v_readlane_b32 s80, v234, 34
	v_readlane_b32 s82, v234, 36
	v_readlane_b32 s84, v234, 38
	v_readlane_b32 s86, v234, 40
	v_readlane_b32 s88, v234, 42
	v_readlane_b32 s76, v234, 44
	v_readlane_b32 s53, v234, 29
	v_readlane_b32 s54, v234, 30
	v_readlane_b32 s34, v234, 31
	v_readlane_b32 s35, v234, 32
	v_readlane_b32 s14, v234, 33
	v_readlane_b32 s81, v234, 35
	v_readlane_b32 s83, v234, 37
	v_readlane_b32 s85, v234, 39
	v_readlane_b32 s87, v234, 41
	v_readlane_b32 s89, v234, 43
	v_readlane_b32 s77, v234, 45
	s_nop 3
	s_mov_b32 s100, 0
	s_nop 1
	v_writelane_b32 v255, s100, 7
	s_mov_b32 s100, 4
	s_branch .Lmg_entry
